# EpiSwiglu epilogue regenerated (same per-element ops, 8 chains issued together, 32-bit store offsets) on top of the site-padded version
# baseline (speedup 1.0000x reference)
; __device__ __forceinline__ unsigned cvt_pk_bf16(float lo, float hi) { unsigned r; asm volatile("v_cvt_pk_bf16_f32 %0, %1, %2" : "=v"(r) : "v"(lo), "v"(hi)); return r; }
; __device__ __forceinline__ float silu_f(float g) { return g * __builtin_amdgcn_rcpf(1.0f + __expf(-g)); }
;     __device__ __forceinline__ void operator()(const f32x4 (&acc)[2][2][4][2], const Unit& u, int wr, int wc, int fr, int fq, const float (&rsv)[8]) const {
;         const int row0 = u.pm * BM + wr * 64 + fr; const int col0 = u.pn * HALF + wc * 32 + 8 * fq;
; #pragma unroll
;         for (int ai = 0; ai < 2; ++ai)
; #pragma unroll
;             for (int m = 0; m < 4; ++m) { bf16_t* rowp = O + (size_t)(row0 + ai * HALF + m * 16) * ldc + col0;
;                 const float rs = __builtin_amdgcn_rsqf(rsv[ai * 4 + m] * (1.0f / 1024.0f) + 1e-6f);
;                 const f32x4 g0 = acc[ai][0][m][0] * rs, g1 = acc[ai][0][m][1] * rs, u0 = acc[ai][1][m][0] * rs, u1 = acc[ai][1][m][1] * rs; u32x4 w;
;                 w.x = cvt_pk_bf16(silu_f(g0[0]) * u0[0], silu_f(g0[1]) * u0[1]); w.y = cvt_pk_bf16(silu_f(g0[2]) * u0[2], silu_f(g0[3]) * u0[3]);
;                 w.z = cvt_pk_bf16(silu_f(g1[0]) * u1[0], silu_f(g1[1]) * u1[1]); w.w = cvt_pk_bf16(silu_f(g1[2]) * u1[2], silu_f(g1[3]) * u1[3]);
;                 __builtin_nontemporal_store(w, (u32x4*)rowp); }
;     }
.LBB0_1108:
	s_waitcnt vmcnt(8)
	v_fmamk_f32 v172, v170, 0x3a800000, v225
	v_fmamk_f32 v174, v169, 0x3a800000, v225
	v_fmamk_f32 v176, v168, 0x3a800000, v225
	v_fmamk_f32 v178, v167, 0x3a800000, v225
	v_fmamk_f32 v180, v166, 0x3a800000, v225
	v_fmamk_f32 v182, v165, 0x3a800000, v225
	v_fmamk_f32 v184, v164, 0x3a800000, v225
	v_fmamk_f32 v186, v163, 0x3a800000, v225
	v_rsq_f32_e32 v172, v172
	v_rsq_f32_e32 v174, v174
	v_rsq_f32_e32 v176, v176
	v_rsq_f32_e32 v178, v178
	v_rsq_f32_e32 v180, v180
	v_rsq_f32_e32 v182, v182
	v_rsq_f32_e32 v184, v184
	v_rsq_f32_e32 v186, v186
	v_lshl_or_b32 v148, s80, 7, v155
	v_lshlrev_b32_e32 v148, 1, v148
	v_mov_b32_e32 v204, v144
	v_or_b32_e32 v205, 16, v144
	v_or_b32_e32 v206, 32, v144
	v_or_b32_e32 v207, 48, v144
	v_add_u32_e32 v208, 0x80, v144
	v_add_u32_e32 v209, 0x90, v144
	v_add_u32_e32 v210, 0xa0, v144
	v_add_u32_e32 v211, 0xb0, v144
	v_mad_u32_u24 v204, v204, s86, v148
	v_mad_u32_u24 v205, v205, s86, v148
	v_mad_u32_u24 v206, v206, s86, v148
	v_mad_u32_u24 v207, v207, s86, v148
	v_mad_u32_u24 v208, v208, s86, v148
	v_mad_u32_u24 v209, v209, s86, v148
	v_mad_u32_u24 v210, v210, s86, v148
	v_mad_u32_u24 v211, v211, s86, v148
	s_andn2_b64 vcc, exec, s[6:7]
	v_pk_mul_f32 v[118:119], v[172:173], v[118:119] op_sel_hi:[0,1]
	v_pk_mul_f32 v[120:121], v[172:173], v[120:121] op_sel_hi:[0,1]
	v_pk_mul_f32 v[122:123], v[172:173], v[122:123] op_sel_hi:[0,1]
	v_pk_mul_f32 v[124:125], v[172:173], v[124:125] op_sel_hi:[0,1]
	v_pk_mul_f32 v[126:127], v[172:173], v[126:127] op_sel_hi:[0,1]
	v_pk_mul_f32 v[128:129], v[172:173], v[128:129] op_sel_hi:[0,1]
	v_pk_mul_f32 v[130:131], v[172:173], v[130:131] op_sel_hi:[0,1]
	v_pk_mul_f32 v[132:133], v[172:173], v[132:133] op_sel_hi:[0,1]
	v_mul_f32_e32 v188, 0xbfb8aa3b, v130
	v_mul_f32_e32 v189, 0xbfb8aa3b, v131
	v_mul_f32_e32 v190, 0xbfb8aa3b, v132
	v_mul_f32_e32 v191, 0xbfb8aa3b, v133
	v_mul_f32_e32 v192, 0xbfb8aa3b, v126
	v_mul_f32_e32 v193, 0xbfb8aa3b, v127
	v_mul_f32_e32 v194, 0xbfb8aa3b, v128
	v_mul_f32_e32 v195, 0xbfb8aa3b, v129
	v_exp_f32_e32 v188, v188
	v_exp_f32_e32 v189, v189
	v_exp_f32_e32 v190, v190
	v_exp_f32_e32 v191, v191
	v_exp_f32_e32 v192, v192
	v_exp_f32_e32 v193, v193
	v_exp_f32_e32 v194, v194
	v_exp_f32_e32 v195, v195
	v_add_f32_e32 v188, 1.0, v188
	v_add_f32_e32 v189, 1.0, v189
	v_add_f32_e32 v190, 1.0, v190
	v_add_f32_e32 v191, 1.0, v191
	v_add_f32_e32 v192, 1.0, v192
	v_add_f32_e32 v193, 1.0, v193
	v_add_f32_e32 v194, 1.0, v194
	v_add_f32_e32 v195, 1.0, v195
	v_rcp_f32_e32 v188, v188
	v_rcp_f32_e32 v189, v189
	v_rcp_f32_e32 v190, v190
	v_rcp_f32_e32 v191, v191
	v_rcp_f32_e32 v192, v192
	v_rcp_f32_e32 v193, v193
	v_rcp_f32_e32 v194, v194
	v_rcp_f32_e32 v195, v195
	v_mul_f32_e32 v188, v130, v188
	v_mul_f32_e32 v189, v131, v189
	v_mul_f32_e32 v190, v132, v190
	v_mul_f32_e32 v191, v133, v191
	v_mul_f32_e32 v192, v126, v192
	v_mul_f32_e32 v193, v127, v193
	v_mul_f32_e32 v194, v128, v194
	v_mul_f32_e32 v195, v129, v195
	v_mul_f32_e32 v188, v188, v122
	v_mul_f32_e32 v189, v189, v123
	v_mul_f32_e32 v190, v190, v124
	v_mul_f32_e32 v191, v191, v125
	v_mul_f32_e32 v192, v192, v118
	v_mul_f32_e32 v193, v193, v119
	v_mul_f32_e32 v194, v194, v120
	v_mul_f32_e32 v195, v195, v121
	v_cvt_pk_bf16_f32 v196, v188, v189
	v_cvt_pk_bf16_f32 v197, v190, v191
	v_cvt_pk_bf16_f32 v198, v192, v193
	v_cvt_pk_bf16_f32 v199, v194, v195
	global_store_dwordx4 v204, v[196:199], s[76:77] nt
	v_pk_mul_f32 v[102:103], v[174:175], v[102:103] op_sel_hi:[0,1]
	v_pk_mul_f32 v[104:105], v[174:175], v[104:105] op_sel_hi:[0,1]
	v_pk_mul_f32 v[106:107], v[174:175], v[106:107] op_sel_hi:[0,1]
	v_pk_mul_f32 v[108:109], v[174:175], v[108:109] op_sel_hi:[0,1]
	v_pk_mul_f32 v[110:111], v[174:175], v[110:111] op_sel_hi:[0,1]
	v_pk_mul_f32 v[112:113], v[174:175], v[112:113] op_sel_hi:[0,1]
	v_pk_mul_f32 v[114:115], v[174:175], v[114:115] op_sel_hi:[0,1]
	v_pk_mul_f32 v[116:117], v[174:175], v[116:117] op_sel_hi:[0,1]
	v_mul_f32_e32 v188, 0xbfb8aa3b, v114
	v_mul_f32_e32 v189, 0xbfb8aa3b, v115
	v_mul_f32_e32 v190, 0xbfb8aa3b, v116
	v_mul_f32_e32 v191, 0xbfb8aa3b, v117
	v_mul_f32_e32 v192, 0xbfb8aa3b, v110
	v_mul_f32_e32 v193, 0xbfb8aa3b, v111
	v_mul_f32_e32 v194, 0xbfb8aa3b, v112
	v_mul_f32_e32 v195, 0xbfb8aa3b, v113
	v_exp_f32_e32 v188, v188
	v_exp_f32_e32 v189, v189
	v_exp_f32_e32 v190, v190
	v_exp_f32_e32 v191, v191
	v_exp_f32_e32 v192, v192
	v_exp_f32_e32 v193, v193
	v_exp_f32_e32 v194, v194
	v_exp_f32_e32 v195, v195
	v_add_f32_e32 v188, 1.0, v188
	v_add_f32_e32 v189, 1.0, v189
	v_add_f32_e32 v190, 1.0, v190
	v_add_f32_e32 v191, 1.0, v191
	v_add_f32_e32 v192, 1.0, v192
	v_add_f32_e32 v193, 1.0, v193
	v_add_f32_e32 v194, 1.0, v194
	v_add_f32_e32 v195, 1.0, v195
	v_rcp_f32_e32 v188, v188
	v_rcp_f32_e32 v189, v189
	v_rcp_f32_e32 v190, v190
	v_rcp_f32_e32 v191, v191
	v_rcp_f32_e32 v192, v192
	v_rcp_f32_e32 v193, v193
	v_rcp_f32_e32 v194, v194
	v_rcp_f32_e32 v195, v195
	v_mul_f32_e32 v188, v114, v188
	v_mul_f32_e32 v189, v115, v189
	v_mul_f32_e32 v190, v116, v190
	v_mul_f32_e32 v191, v117, v191
	v_mul_f32_e32 v192, v110, v192
	v_mul_f32_e32 v193, v111, v193
	v_mul_f32_e32 v194, v112, v194
	v_mul_f32_e32 v195, v113, v195
	v_mul_f32_e32 v188, v188, v106
	v_mul_f32_e32 v189, v189, v107
	v_mul_f32_e32 v190, v190, v108
	v_mul_f32_e32 v191, v191, v109
	v_mul_f32_e32 v192, v192, v102
	v_mul_f32_e32 v193, v193, v103
	v_mul_f32_e32 v194, v194, v104
	v_mul_f32_e32 v195, v195, v105
	v_cvt_pk_bf16_f32 v200, v188, v189
	v_cvt_pk_bf16_f32 v201, v190, v191
	v_cvt_pk_bf16_f32 v202, v192, v193
	v_cvt_pk_bf16_f32 v203, v194, v195
	global_store_dwordx4 v205, v[200:203], s[76:77] nt
	v_pk_mul_f32 v[86:87], v[176:177], v[86:87] op_sel_hi:[0,1]
; __device__ __forceinline__ unsigned cvt_pk_bf16(float lo, float hi) { unsigned r; asm volatile("v_cvt_pk_bf16_f32 %0, %1, %2" : "=v"(r) : "v"(lo), "v"(hi)); return r; }
; __device__ __forceinline__ float silu_f(float g) { return g * __builtin_amdgcn_rcpf(1.0f + __expf(-g)); }
;     __device__ __forceinline__ void operator()(const f32x4 (&acc)[2][2][4][2], const Unit& u, int wr, int wc, int fr, int fq, const float (&rsv)[8]) const {
;         const int row0 = u.pm * BM + wr * 64 + fr; const int col0 = u.pn * HALF + wc * 32 + 8 * fq;
; #pragma unroll
;         for (int ai = 0; ai < 2; ++ai)
; #pragma unroll
;             for (int m = 0; m < 4; ++m) { bf16_t* rowp = O + (size_t)(row0 + ai * HALF + m * 16) * ldc + col0;
;                 const float rs = __builtin_amdgcn_rsqf(rsv[ai * 4 + m] * (1.0f / 1024.0f) + 1e-6f);
;                 const f32x4 g0 = acc[ai][0][m][0] * rs, g1 = acc[ai][0][m][1] * rs, u0 = acc[ai][1][m][0] * rs, u1 = acc[ai][1][m][1] * rs; u32x4 w;
;                 w.x = cvt_pk_bf16(silu_f(g0[0]) * u0[0], silu_f(g0[1]) * u0[1]); w.y = cvt_pk_bf16(silu_f(g0[2]) * u0[2], silu_f(g0[3]) * u0[3]);
;                 w.z = cvt_pk_bf16(silu_f(g1[0]) * u1[0], silu_f(g1[1]) * u1[1]); w.w = cvt_pk_bf16(silu_f(g1[2]) * u1[2], silu_f(g1[3]) * u1[3]);
;                 __builtin_nontemporal_store(w, (u32x4*)rowp); }
;     }
	v_pk_mul_f32 v[88:89], v[176:177], v[88:89] op_sel_hi:[0,1]
	v_pk_mul_f32 v[90:91], v[176:177], v[90:91] op_sel_hi:[0,1]
	v_pk_mul_f32 v[92:93], v[176:177], v[92:93] op_sel_hi:[0,1]
	v_pk_mul_f32 v[94:95], v[176:177], v[94:95] op_sel_hi:[0,1]
	v_pk_mul_f32 v[96:97], v[176:177], v[96:97] op_sel_hi:[0,1]
	v_pk_mul_f32 v[98:99], v[176:177], v[98:99] op_sel_hi:[0,1]
	v_pk_mul_f32 v[100:101], v[176:177], v[100:101] op_sel_hi:[0,1]
	v_mul_f32_e32 v188, 0xbfb8aa3b, v98
	v_mul_f32_e32 v189, 0xbfb8aa3b, v99
	v_mul_f32_e32 v190, 0xbfb8aa3b, v100
	v_mul_f32_e32 v191, 0xbfb8aa3b, v101
	v_mul_f32_e32 v192, 0xbfb8aa3b, v94
	v_mul_f32_e32 v193, 0xbfb8aa3b, v95
	v_mul_f32_e32 v194, 0xbfb8aa3b, v96
	v_mul_f32_e32 v195, 0xbfb8aa3b, v97
	v_exp_f32_e32 v188, v188
	v_exp_f32_e32 v189, v189
	v_exp_f32_e32 v190, v190
	v_exp_f32_e32 v191, v191
	v_exp_f32_e32 v192, v192
	v_exp_f32_e32 v193, v193
	v_exp_f32_e32 v194, v194
	v_exp_f32_e32 v195, v195
	v_add_f32_e32 v188, 1.0, v188
	v_add_f32_e32 v189, 1.0, v189
	v_add_f32_e32 v190, 1.0, v190
	v_add_f32_e32 v191, 1.0, v191
	v_add_f32_e32 v192, 1.0, v192
	v_add_f32_e32 v193, 1.0, v193
	v_add_f32_e32 v194, 1.0, v194
	v_add_f32_e32 v195, 1.0, v195
	v_rcp_f32_e32 v188, v188
	v_rcp_f32_e32 v189, v189
	v_rcp_f32_e32 v190, v190
	v_rcp_f32_e32 v191, v191
	v_rcp_f32_e32 v192, v192
	v_rcp_f32_e32 v193, v193
	v_rcp_f32_e32 v194, v194
	v_rcp_f32_e32 v195, v195
	v_mul_f32_e32 v188, v98, v188
	v_mul_f32_e32 v189, v99, v189
	v_mul_f32_e32 v190, v100, v190
	v_mul_f32_e32 v191, v101, v191
	v_mul_f32_e32 v192, v94, v192
	v_mul_f32_e32 v193, v95, v193
	v_mul_f32_e32 v194, v96, v194
	v_mul_f32_e32 v195, v97, v195
	v_mul_f32_e32 v188, v188, v90
	v_mul_f32_e32 v189, v189, v91
	v_mul_f32_e32 v190, v190, v92
	v_mul_f32_e32 v191, v191, v93
	v_mul_f32_e32 v192, v192, v86
	v_mul_f32_e32 v193, v193, v87
	v_mul_f32_e32 v194, v194, v88
	v_mul_f32_e32 v195, v195, v89
	v_cvt_pk_bf16_f32 v196, v188, v189
	v_cvt_pk_bf16_f32 v197, v190, v191
	v_cvt_pk_bf16_f32 v198, v192, v193
	v_cvt_pk_bf16_f32 v199, v194, v195
	global_store_dwordx4 v206, v[196:199], s[76:77] nt
	v_pk_mul_f32 v[70:71], v[178:179], v[70:71] op_sel_hi:[0,1]
	v_pk_mul_f32 v[72:73], v[178:179], v[72:73] op_sel_hi:[0,1]
	v_pk_mul_f32 v[74:75], v[178:179], v[74:75] op_sel_hi:[0,1]
	v_pk_mul_f32 v[76:77], v[178:179], v[76:77] op_sel_hi:[0,1]
	v_pk_mul_f32 v[78:79], v[178:179], v[78:79] op_sel_hi:[0,1]
	v_pk_mul_f32 v[80:81], v[178:179], v[80:81] op_sel_hi:[0,1]
	v_pk_mul_f32 v[82:83], v[178:179], v[82:83] op_sel_hi:[0,1]
	v_pk_mul_f32 v[84:85], v[178:179], v[84:85] op_sel_hi:[0,1]
	v_mul_f32_e32 v188, 0xbfb8aa3b, v82
	v_mul_f32_e32 v189, 0xbfb8aa3b, v83
	v_mul_f32_e32 v190, 0xbfb8aa3b, v84
	v_mul_f32_e32 v191, 0xbfb8aa3b, v85
	v_mul_f32_e32 v192, 0xbfb8aa3b, v78
	v_mul_f32_e32 v193, 0xbfb8aa3b, v79
	v_mul_f32_e32 v194, 0xbfb8aa3b, v80
	v_mul_f32_e32 v195, 0xbfb8aa3b, v81
	v_exp_f32_e32 v188, v188
	v_exp_f32_e32 v189, v189
	v_exp_f32_e32 v190, v190
	v_exp_f32_e32 v191, v191
	v_exp_f32_e32 v192, v192
	v_exp_f32_e32 v193, v193
	v_exp_f32_e32 v194, v194
	v_exp_f32_e32 v195, v195
	v_add_f32_e32 v188, 1.0, v188
	v_add_f32_e32 v189, 1.0, v189
	v_add_f32_e32 v190, 1.0, v190
	v_add_f32_e32 v191, 1.0, v191
	v_add_f32_e32 v192, 1.0, v192
	v_add_f32_e32 v193, 1.0, v193
	v_add_f32_e32 v194, 1.0, v194
	v_add_f32_e32 v195, 1.0, v195
	v_rcp_f32_e32 v188, v188
	v_rcp_f32_e32 v189, v189
	v_rcp_f32_e32 v190, v190
	v_rcp_f32_e32 v191, v191
	v_rcp_f32_e32 v192, v192
	v_rcp_f32_e32 v193, v193
	v_rcp_f32_e32 v194, v194
	v_rcp_f32_e32 v195, v195
	v_mul_f32_e32 v188, v82, v188
	v_mul_f32_e32 v189, v83, v189
	v_mul_f32_e32 v190, v84, v190
	v_mul_f32_e32 v191, v85, v191
	v_mul_f32_e32 v192, v78, v192
	v_mul_f32_e32 v193, v79, v193
	v_mul_f32_e32 v194, v80, v194
	v_mul_f32_e32 v195, v81, v195
	v_mul_f32_e32 v188, v188, v74
	v_mul_f32_e32 v189, v189, v75
	v_mul_f32_e32 v190, v190, v76
	v_mul_f32_e32 v191, v191, v77
	v_mul_f32_e32 v192, v192, v70
	v_mul_f32_e32 v193, v193, v71
	v_mul_f32_e32 v194, v194, v72
	v_mul_f32_e32 v195, v195, v73
	v_cvt_pk_bf16_f32 v200, v188, v189
	v_cvt_pk_bf16_f32 v201, v190, v191
	v_cvt_pk_bf16_f32 v202, v192, v193
	v_cvt_pk_bf16_f32 v203, v194, v195
	global_store_dwordx4 v207, v[200:203], s[76:77] nt
	v_pk_mul_f32 v[54:55], v[180:181], v[54:55] op_sel_hi:[0,1]
	v_pk_mul_f32 v[56:57], v[180:181], v[56:57] op_sel_hi:[0,1]
	v_pk_mul_f32 v[58:59], v[180:181], v[58:59] op_sel_hi:[0,1]
	v_pk_mul_f32 v[60:61], v[180:181], v[60:61] op_sel_hi:[0,1]
	v_pk_mul_f32 v[62:63], v[180:181], v[62:63] op_sel_hi:[0,1]
	v_pk_mul_f32 v[64:65], v[180:181], v[64:65] op_sel_hi:[0,1]
	v_pk_mul_f32 v[66:67], v[180:181], v[66:67] op_sel_hi:[0,1]
	v_pk_mul_f32 v[68:69], v[180:181], v[68:69] op_sel_hi:[0,1]
	v_mul_f32_e32 v188, 0xbfb8aa3b, v66
	v_mul_f32_e32 v189, 0xbfb8aa3b, v67
	v_mul_f32_e32 v190, 0xbfb8aa3b, v68
	v_mul_f32_e32 v191, 0xbfb8aa3b, v69
	v_mul_f32_e32 v192, 0xbfb8aa3b, v62
	v_mul_f32_e32 v193, 0xbfb8aa3b, v63
	v_mul_f32_e32 v194, 0xbfb8aa3b, v64
	v_mul_f32_e32 v195, 0xbfb8aa3b, v65
	v_exp_f32_e32 v188, v188
	v_exp_f32_e32 v189, v189
	v_exp_f32_e32 v190, v190
	v_exp_f32_e32 v191, v191
	v_exp_f32_e32 v192, v192
	v_exp_f32_e32 v193, v193
	v_exp_f32_e32 v194, v194
	v_exp_f32_e32 v195, v195
	v_add_f32_e32 v188, 1.0, v188
	v_add_f32_e32 v189, 1.0, v189
	v_add_f32_e32 v190, 1.0, v190
	v_add_f32_e32 v191, 1.0, v191
	v_add_f32_e32 v192, 1.0, v192
	v_add_f32_e32 v193, 1.0, v193
	v_add_f32_e32 v194, 1.0, v194
	v_add_f32_e32 v195, 1.0, v195
	v_rcp_f32_e32 v188, v188
	v_rcp_f32_e32 v189, v189
	v_rcp_f32_e32 v190, v190
	v_rcp_f32_e32 v191, v191
	v_rcp_f32_e32 v192, v192
	v_rcp_f32_e32 v193, v193
	v_rcp_f32_e32 v194, v194
; __device__ __forceinline__ unsigned cvt_pk_bf16(float lo, float hi) { unsigned r; asm volatile("v_cvt_pk_bf16_f32 %0, %1, %2" : "=v"(r) : "v"(lo), "v"(hi)); return r; }
; __device__ __forceinline__ float silu_f(float g) { return g * __builtin_amdgcn_rcpf(1.0f + __expf(-g)); }
;     __device__ __forceinline__ void operator()(const f32x4 (&acc)[2][2][4][2], const Unit& u, int wr, int wc, int fr, int fq, const float (&rsv)[8]) const {
;         const int row0 = u.pm * BM + wr * 64 + fr; const int col0 = u.pn * HALF + wc * 32 + 8 * fq;
; #pragma unroll
;         for (int ai = 0; ai < 2; ++ai)
; #pragma unroll
;             for (int m = 0; m < 4; ++m) { bf16_t* rowp = O + (size_t)(row0 + ai * HALF + m * 16) * ldc + col0;
;                 const float rs = __builtin_amdgcn_rsqf(rsv[ai * 4 + m] * (1.0f / 1024.0f) + 1e-6f);
;                 const f32x4 g0 = acc[ai][0][m][0] * rs, g1 = acc[ai][0][m][1] * rs, u0 = acc[ai][1][m][0] * rs, u1 = acc[ai][1][m][1] * rs; u32x4 w;
;                 w.x = cvt_pk_bf16(silu_f(g0[0]) * u0[0], silu_f(g0[1]) * u0[1]); w.y = cvt_pk_bf16(silu_f(g0[2]) * u0[2], silu_f(g0[3]) * u0[3]);
;                 w.z = cvt_pk_bf16(silu_f(g1[0]) * u1[0], silu_f(g1[1]) * u1[1]); w.w = cvt_pk_bf16(silu_f(g1[2]) * u1[2], silu_f(g1[3]) * u1[3]);
;                 __builtin_nontemporal_store(w, (u32x4*)rowp); }
;     }
	v_rcp_f32_e32 v195, v195
	v_mul_f32_e32 v188, v66, v188
	v_mul_f32_e32 v189, v67, v189
	v_mul_f32_e32 v190, v68, v190
	v_mul_f32_e32 v191, v69, v191
	v_mul_f32_e32 v192, v62, v192
	v_mul_f32_e32 v193, v63, v193
	v_mul_f32_e32 v194, v64, v194
	v_mul_f32_e32 v195, v65, v195
	v_mul_f32_e32 v188, v188, v58
	v_mul_f32_e32 v189, v189, v59
	v_mul_f32_e32 v190, v190, v60
	v_mul_f32_e32 v191, v191, v61
	v_mul_f32_e32 v192, v192, v54
	v_mul_f32_e32 v193, v193, v55
	v_mul_f32_e32 v194, v194, v56
	v_mul_f32_e32 v195, v195, v57
	v_cvt_pk_bf16_f32 v196, v188, v189
	v_cvt_pk_bf16_f32 v197, v190, v191
	v_cvt_pk_bf16_f32 v198, v192, v193
	v_cvt_pk_bf16_f32 v199, v194, v195
	global_store_dwordx4 v208, v[196:199], s[76:77] nt
	v_pk_mul_f32 v[38:39], v[182:183], v[38:39] op_sel_hi:[0,1]
	v_pk_mul_f32 v[40:41], v[182:183], v[40:41] op_sel_hi:[0,1]
	v_pk_mul_f32 v[42:43], v[182:183], v[42:43] op_sel_hi:[0,1]
	v_pk_mul_f32 v[44:45], v[182:183], v[44:45] op_sel_hi:[0,1]
	v_pk_mul_f32 v[46:47], v[182:183], v[46:47] op_sel_hi:[0,1]
	v_pk_mul_f32 v[48:49], v[182:183], v[48:49] op_sel_hi:[0,1]
	v_pk_mul_f32 v[50:51], v[182:183], v[50:51] op_sel_hi:[0,1]
	v_pk_mul_f32 v[52:53], v[182:183], v[52:53] op_sel_hi:[0,1]
	v_mul_f32_e32 v188, 0xbfb8aa3b, v50
	v_mul_f32_e32 v189, 0xbfb8aa3b, v51
	v_mul_f32_e32 v190, 0xbfb8aa3b, v52
	v_mul_f32_e32 v191, 0xbfb8aa3b, v53
	v_mul_f32_e32 v192, 0xbfb8aa3b, v46
	v_mul_f32_e32 v193, 0xbfb8aa3b, v47
	v_mul_f32_e32 v194, 0xbfb8aa3b, v48
	v_mul_f32_e32 v195, 0xbfb8aa3b, v49
	v_exp_f32_e32 v188, v188
	v_exp_f32_e32 v189, v189
	v_exp_f32_e32 v190, v190
	v_exp_f32_e32 v191, v191
	v_exp_f32_e32 v192, v192
	v_exp_f32_e32 v193, v193
	v_exp_f32_e32 v194, v194
	v_exp_f32_e32 v195, v195
	v_add_f32_e32 v188, 1.0, v188
	v_add_f32_e32 v189, 1.0, v189
	v_add_f32_e32 v190, 1.0, v190
	v_add_f32_e32 v191, 1.0, v191
	v_add_f32_e32 v192, 1.0, v192
	v_add_f32_e32 v193, 1.0, v193
	v_add_f32_e32 v194, 1.0, v194
	v_add_f32_e32 v195, 1.0, v195
	v_rcp_f32_e32 v188, v188
	v_rcp_f32_e32 v189, v189
	v_rcp_f32_e32 v190, v190
	v_rcp_f32_e32 v191, v191
	v_rcp_f32_e32 v192, v192
	v_rcp_f32_e32 v193, v193
	v_rcp_f32_e32 v194, v194
	v_rcp_f32_e32 v195, v195
	v_mul_f32_e32 v188, v50, v188
	v_mul_f32_e32 v189, v51, v189
	v_mul_f32_e32 v190, v52, v190
	v_mul_f32_e32 v191, v53, v191
	v_mul_f32_e32 v192, v46, v192
	v_mul_f32_e32 v193, v47, v193
	v_mul_f32_e32 v194, v48, v194
	v_mul_f32_e32 v195, v49, v195
	v_mul_f32_e32 v188, v188, v42
	v_mul_f32_e32 v189, v189, v43
	v_mul_f32_e32 v190, v190, v44
	v_mul_f32_e32 v191, v191, v45
	v_mul_f32_e32 v192, v192, v38
	v_mul_f32_e32 v193, v193, v39
	v_mul_f32_e32 v194, v194, v40
	v_mul_f32_e32 v195, v195, v41
	v_cvt_pk_bf16_f32 v200, v188, v189
	v_cvt_pk_bf16_f32 v201, v190, v191
	v_cvt_pk_bf16_f32 v202, v192, v193
	v_cvt_pk_bf16_f32 v203, v194, v195
	global_store_dwordx4 v209, v[200:203], s[76:77] nt
	v_pk_mul_f32 v[22:23], v[184:185], v[22:23] op_sel_hi:[0,1]
	v_pk_mul_f32 v[24:25], v[184:185], v[24:25] op_sel_hi:[0,1]
	v_pk_mul_f32 v[26:27], v[184:185], v[26:27] op_sel_hi:[0,1]
	v_pk_mul_f32 v[28:29], v[184:185], v[28:29] op_sel_hi:[0,1]
	v_pk_mul_f32 v[30:31], v[184:185], v[30:31] op_sel_hi:[0,1]
	v_pk_mul_f32 v[32:33], v[184:185], v[32:33] op_sel_hi:[0,1]
	v_pk_mul_f32 v[34:35], v[184:185], v[34:35] op_sel_hi:[0,1]
	v_pk_mul_f32 v[36:37], v[184:185], v[36:37] op_sel_hi:[0,1]
	v_mul_f32_e32 v188, 0xbfb8aa3b, v34
	v_mul_f32_e32 v189, 0xbfb8aa3b, v35
	v_mul_f32_e32 v190, 0xbfb8aa3b, v36
	v_mul_f32_e32 v191, 0xbfb8aa3b, v37
	v_mul_f32_e32 v192, 0xbfb8aa3b, v30
	v_mul_f32_e32 v193, 0xbfb8aa3b, v31
	v_mul_f32_e32 v194, 0xbfb8aa3b, v32
	v_mul_f32_e32 v195, 0xbfb8aa3b, v33
	v_exp_f32_e32 v188, v188
	v_exp_f32_e32 v189, v189
	v_exp_f32_e32 v190, v190
	v_exp_f32_e32 v191, v191
	v_exp_f32_e32 v192, v192
	v_exp_f32_e32 v193, v193
	v_exp_f32_e32 v194, v194
; __device__ __forceinline__ unsigned cvt_pk_bf16(float lo, float hi) { unsigned r; asm volatile("v_cvt_pk_bf16_f32 %0, %1, %2" : "=v"(r) : "v"(lo), "v"(hi)); return r; }
; __device__ __forceinline__ float silu_f(float g) { return g * __builtin_amdgcn_rcpf(1.0f + __expf(-g)); }
;     __device__ __forceinline__ void operator()(const f32x4 (&acc)[2][2][4][2], const Unit& u, int wr, int wc, int fr, int fq, const float (&rsv)[8]) const {
;         const int row0 = u.pm * BM + wr * 64 + fr; const int col0 = u.pn * HALF + wc * 32 + 8 * fq;
; #pragma unroll
;         for (int ai = 0; ai < 2; ++ai)
; #pragma unroll
;             for (int m = 0; m < 4; ++m) { bf16_t* rowp = O + (size_t)(row0 + ai * HALF + m * 16) * ldc + col0;
;                 const float rs = __builtin_amdgcn_rsqf(rsv[ai * 4 + m] * (1.0f / 1024.0f) + 1e-6f);
;                 const f32x4 g0 = acc[ai][0][m][0] * rs, g1 = acc[ai][0][m][1] * rs, u0 = acc[ai][1][m][0] * rs, u1 = acc[ai][1][m][1] * rs; u32x4 w;
;                 w.x = cvt_pk_bf16(silu_f(g0[0]) * u0[0], silu_f(g0[1]) * u0[1]); w.y = cvt_pk_bf16(silu_f(g0[2]) * u0[2], silu_f(g0[3]) * u0[3]);
;                 w.z = cvt_pk_bf16(silu_f(g1[0]) * u1[0], silu_f(g1[1]) * u1[1]); w.w = cvt_pk_bf16(silu_f(g1[2]) * u1[2], silu_f(g1[3]) * u1[3]);
;                 __builtin_nontemporal_store(w, (u32x4*)rowp); }
;     }
	v_exp_f32_e32 v195, v195
	v_add_f32_e32 v188, 1.0, v188
	v_add_f32_e32 v189, 1.0, v189
	v_add_f32_e32 v190, 1.0, v190
	v_add_f32_e32 v191, 1.0, v191
	v_add_f32_e32 v192, 1.0, v192
	v_add_f32_e32 v193, 1.0, v193
	v_add_f32_e32 v194, 1.0, v194
	v_add_f32_e32 v195, 1.0, v195
	v_rcp_f32_e32 v188, v188
	v_rcp_f32_e32 v189, v189
	v_rcp_f32_e32 v190, v190
	v_rcp_f32_e32 v191, v191
	v_rcp_f32_e32 v192, v192
	v_rcp_f32_e32 v193, v193
	v_rcp_f32_e32 v194, v194
	v_rcp_f32_e32 v195, v195
	v_mul_f32_e32 v188, v34, v188
	v_mul_f32_e32 v189, v35, v189
	v_mul_f32_e32 v190, v36, v190
	v_mul_f32_e32 v191, v37, v191
	v_mul_f32_e32 v192, v30, v192
	v_mul_f32_e32 v193, v31, v193
	v_mul_f32_e32 v194, v32, v194
	v_mul_f32_e32 v195, v33, v195
	v_mul_f32_e32 v188, v188, v26
	v_mul_f32_e32 v189, v189, v27
	v_mul_f32_e32 v190, v190, v28
	v_mul_f32_e32 v191, v191, v29
	v_mul_f32_e32 v192, v192, v22
	v_mul_f32_e32 v193, v193, v23
	v_mul_f32_e32 v194, v194, v24
	v_mul_f32_e32 v195, v195, v25
	v_cvt_pk_bf16_f32 v196, v188, v189
	v_cvt_pk_bf16_f32 v197, v190, v191
	v_cvt_pk_bf16_f32 v198, v192, v193
	v_cvt_pk_bf16_f32 v199, v194, v195
	global_store_dwordx4 v210, v[196:199], s[76:77] nt
	v_pk_mul_f32 v[6:7], v[186:187], v[6:7] op_sel_hi:[0,1]
	v_pk_mul_f32 v[8:9], v[186:187], v[8:9] op_sel_hi:[0,1]
	v_pk_mul_f32 v[10:11], v[186:187], v[10:11] op_sel_hi:[0,1]
	v_pk_mul_f32 v[12:13], v[186:187], v[12:13] op_sel_hi:[0,1]
	v_pk_mul_f32 v[14:15], v[186:187], v[14:15] op_sel_hi:[0,1]
	v_pk_mul_f32 v[16:17], v[186:187], v[16:17] op_sel_hi:[0,1]
	v_pk_mul_f32 v[18:19], v[186:187], v[18:19] op_sel_hi:[0,1]
	v_pk_mul_f32 v[20:21], v[186:187], v[20:21] op_sel_hi:[0,1]
	v_mul_f32_e32 v188, 0xbfb8aa3b, v18
	v_mul_f32_e32 v189, 0xbfb8aa3b, v19
	v_mul_f32_e32 v190, 0xbfb8aa3b, v20
	v_mul_f32_e32 v191, 0xbfb8aa3b, v21
	v_mul_f32_e32 v192, 0xbfb8aa3b, v14
	v_mul_f32_e32 v193, 0xbfb8aa3b, v15
	v_mul_f32_e32 v194, 0xbfb8aa3b, v16
	v_mul_f32_e32 v195, 0xbfb8aa3b, v17
	v_exp_f32_e32 v188, v188
	v_exp_f32_e32 v189, v189
	v_exp_f32_e32 v190, v190
	v_exp_f32_e32 v191, v191
	v_exp_f32_e32 v192, v192
	v_exp_f32_e32 v193, v193
	v_exp_f32_e32 v194, v194
	v_exp_f32_e32 v195, v195
	v_add_f32_e32 v188, 1.0, v188
	v_add_f32_e32 v189, 1.0, v189
	v_add_f32_e32 v190, 1.0, v190
	v_add_f32_e32 v191, 1.0, v191
	v_add_f32_e32 v192, 1.0, v192
	v_add_f32_e32 v193, 1.0, v193
	v_add_f32_e32 v194, 1.0, v194
	v_add_f32_e32 v195, 1.0, v195
	v_rcp_f32_e32 v188, v188
	v_rcp_f32_e32 v189, v189
	v_rcp_f32_e32 v190, v190
	v_rcp_f32_e32 v191, v191
	v_rcp_f32_e32 v192, v192
	v_rcp_f32_e32 v193, v193
	v_rcp_f32_e32 v194, v194
	v_rcp_f32_e32 v195, v195
	v_mul_f32_e32 v188, v18, v188
	v_mul_f32_e32 v189, v19, v189
	v_mul_f32_e32 v190, v20, v190
	v_mul_f32_e32 v191, v21, v191
	v_mul_f32_e32 v192, v14, v192
	v_mul_f32_e32 v193, v15, v193
	v_mul_f32_e32 v194, v16, v194
	v_mul_f32_e32 v195, v17, v195
	v_mul_f32_e32 v188, v188, v10
	v_mul_f32_e32 v189, v189, v11
	v_mul_f32_e32 v190, v190, v12
	v_mul_f32_e32 v191, v191, v13
	v_mul_f32_e32 v192, v192, v6
	v_mul_f32_e32 v193, v193, v7
	v_mul_f32_e32 v194, v194, v8
	v_mul_f32_e32 v195, v195, v9
	v_cvt_pk_bf16_f32 v200, v188, v189
	v_cvt_pk_bf16_f32 v201, v190, v191
	v_cvt_pk_bf16_f32 v202, v192, v193
	v_cvt_pk_bf16_f32 v203, v194, v195
	global_store_dwordx4 v211, v[200:203], s[76:77] nt
	s_mov_b64 s[4:5], -1
	s_branch .Lepisw_pad_end
	s_nop 0
	s_nop 0
	s_nop 0
	s_nop 0
	s_nop 0
	s_nop 0
	s_nop 0
	s_nop 0
	s_nop 0
	s_nop 0
	s_nop 0
	s_nop 0
	s_nop 0
	s_nop 0
	s_nop 0
	s_nop 0
	s_nop 0
	s_nop 0
	s_nop 0
	s_nop 0
	s_nop 0
	s_nop 0
	s_nop 0
	s_nop 0
	s_nop 0
	s_nop 0
	s_nop 0
	s_nop 0
	s_nop 0
	s_nop 0
	s_nop 0
	s_nop 0
	s_nop 0
	s_nop 0
	s_nop 0
	s_nop 0
	s_nop 0
	s_nop 0
	s_nop 0
	s_nop 0
	s_nop 0
	s_nop 0
	s_nop 0
	s_nop 0
	s_nop 0
	s_nop 0
	s_nop 0
	s_nop 0
	s_nop 0
	s_nop 0
	s_nop 0
	s_nop 0
	s_nop 0
	s_nop 0
	s_nop 0
